# priority raise kept for mLSTM and SSD items only: s_setprio 0 when a workgroup starts its attention items
# speedup vs baseline: 1.0014x; 1.0014x over previous
; #define LAS __attribute__((address_space(3)))
;     DI bf16_t* fP() const { return (bf16_t*)(ws + WS_P); }
;     DI float* fROPE() const { return (float*)(ws + WS_ROPE); }
; DI void attn_item(const Params& p, const Ctx& c, int l, int S, int tokbase, int qb, int kvh) {
;     int tid_l = threadIdx.x; asm volatile("" : "+v"(tid_l));
;     const int tid = tid_l, lane = tid & 63, w = __builtin_amdgcn_readfirstlane(tid >> 6), lr = lane & 15, lg = lane >> 4;
;     LAS bf16_t* Ks = (LAS bf16_t*)c.lds; LAS bf16_t* VTs = Ks + 384 * KP;
;     const int kstart = qb * 128 - 128;
;     const float* qg = p.in[4] + l * 64; const float* kg = p.in[5] + l * 64;
;     if (tid < 384) {
;         const int kpos = kstart + tid; float f[64];
;         if (kpos >= 0 && kpos < S) {
;             const bf16_t* kp = c.fP() + (size_t)(tokbase + kpos) * P1LD + 512 + kvh * 64;
; #pragma unroll
;             for (int i = 0; i < 8; ++i) unpack8(*(const u32x4*)(kp + 8 * i), f + 8 * i);
;             norm_rope64(f, kg, c.fROPE() + kpos * 16);
; DI void phase_mixers(const Params& p, const Ctx& c, int l, int g) {
;     ...
;         if (threadIdx.x == 0) sitem[0] = (int)atomicAdd(ctr, 1u);
;         __syncthreads();
;         const int it = sitem[0];
;         __syncthreads();
;         if (it >= total) break;
;         if (it < nml) { const int eh = it & 1, head = (it >> 1) & 3, dir = (it >> 3) & 1, seq = it >> 4; mlstm_item(p, c, l, S, seq * S, dir, head, eh); }
;         else if (it < nml + nssd) { const int j = it - nml, head = j & 7, dir = (j >> 3) & 1, seq = j >> 4; ssd_item(p, c, l, S, seq * S, dir, head); }
;         else { const int j = it - nml - nssd, kvh = j & 1, qb = (j >> 1) % nqb, seq = (j >> 1) / nqb; attn_item(p, c, l, S, seq * S, qb, kvh); }
.LBB0_296:
	s_mov_b32 s79, 0x800000
	s_or_b64 exec, exec, s[36:37]
	v_readlane_b32 s2, v253, 47
	s_waitcnt lgkmcnt(0)
	s_barrier
	v_mov_b32_e32 v1, s2
	ds_read_b32 v1, v1
	s_mov_b64 s[36:37], -1
	s_waitcnt lgkmcnt(0)
	s_barrier
	v_cmp_le_i32_e32 vcc, s35, v1
	v_readfirstlane_b32 s23, v1
	s_cbranch_vccnz .LBB0_291
	v_readlane_b32 s2, v253, 59
	s_cmp_ge_i32 s23, s2
	s_cbranch_scc0 .LBB0_461
	v_readlane_b32 s2, v255, 6
	s_cmp_ge_i32 s23, s2
	s_cbranch_scc0 .LBB0_324
	s_setprio 0
	v_readlane_b32 s2, v255, 9
	s_add_i32 s2, s23, s2
	s_ashr_i32 s2, s2, 1
	s_abs_i32 s21, s2
	v_readlane_b32 s24, v255, 12
	s_mul_hi_u32 s24, s21, s24
	s_mul_i32 s25, s24, s34
	s_sub_i32 s21, s21, s25
	s_and_b32 s40, s23, 1
	s_ashr_i32 s20, s2, 31
	s_add_i32 s25, s24, 1
	s_sub_i32 s26, s21, s34
	s_cmp_ge_u32 s21, s34
	s_cselect_b32 s24, s25, s24
	s_cselect_b32 s21, s26, s21
	s_add_i32 s25, s24, 1
	s_cmp_ge_u32 s21, s34
	s_cselect_b32 s21, s25, s24
	s_xor_b32 s21, s21, s20
	s_sub_i32 s20, s21, s20
	s_mul_i32 s21, s20, s34
	s_sub_i32 s24, s2, s21
	v_readlane_b32 s21, v255, 10
	v_mov_b32_e32 v138, v167
	s_lshl_b32 s31, s24, 7
	s_movk_i32 s26, 0x180
	s_lshl_b32 s21, s20, s21
	s_add_i32 s25, s31, 0xffffff80
	v_readfirstlane_b32 s33, v138
	v_cmp_gt_i32_e32 vcc, s26, v138
	s_and_saveexec_b64 s[36:37], vcc
	s_cbranch_execz .LBB0_303
	v_add_u32_e32 v1, s25, v138
	v_cmp_gt_u32_e32 vcc, s30, v1
	s_waitcnt vmcnt(4)
	v_mov_b32_e32 v5, 0
	v_mov_b32_e32 v4, 0
	v_mov_b32_e32 v3, 0
	v_mov_b32_e32 v2, 0
	v_mov_b32_e32 v13, 0
	v_mov_b32_e32 v12, 0
	v_mov_b32_e32 v11, 0
	v_mov_b32_e32 v10, 0
	v_mov_b32_e32 v9, 0
	v_mov_b32_e32 v8, 0
	v_mov_b32_e32 v7, 0
	v_mov_b32_e32 v6, 0
	v_mov_b32_e32 v17, 0
	v_mov_b32_e32 v16, 0
	v_mov_b32_e32 v15, 0
	v_mov_b32_e32 v14, 0
	v_mov_b32_e32 v21, 0
	v_mov_b32_e32 v20, 0
	v_mov_b32_e32 v19, 0
	v_mov_b32_e32 v18, 0
	v_mov_b32_e32 v29, 0
	v_mov_b32_e32 v28, 0
	v_mov_b32_e32 v27, 0
	v_mov_b32_e32 v26, 0
	v_mov_b32_e32 v22, 0
	v_mov_b32_e32 v23, 0
	v_mov_b32_e32 v24, 0
	v_mov_b32_e32 v25, 0
	v_mov_b32_e32 v30, 0
	v_mov_b32_e32 v31, 0
	v_mov_b32_e32 v32, 0
	v_mov_b32_e32 v33, 0
	s_and_saveexec_b64 s[38:39], vcc
	s_cbranch_execz .LBB0_302
	v_add_u32_e32 v4, s21, v1
	v_mov_b64_e32 v[2:3], s[92:93]
	v_mad_i64_i32 v[2:3], s[42:43], v4, s19, v[2:3]
	s_lshl_b32 s74, s40, 7
	v_lshl_add_u64 v[2:3], v[2:3], 0, s[74:75]
	s_mov_b64 s[42:43], 0x4000400
	v_lshl_add_u64 v[58:59], v[2:3], 0, s[42:43]
	v_add_co_u32_e32 v2, vcc, 0x4000000, v2
	global_load_dwordx4 v[66:69], v[58:59], off offset:16
	global_load_dwordx4 v[70:73], v[58:59], off offset:80
	global_load_dwordx4 v[100:103], v[58:59], off offset:64
	v_addc_co_u32_e32 v3, vcc, 0, v3, vcc
	global_load_dwordx4 v[54:57], v[58:59], off offset:48
	global_load_dwordx4 v[106:109], v[2:3], off offset:1024
	global_load_dwordx4 v[50:53], v[58:59], off offset:32
	v_readlane_b32 s42, v254, 25
	v_lshlrev_b32_e32 v6, 4, v1
	v_mov_b32_e32 v7, v0
	v_readlane_b32 s44, v254, 56
	v_readlane_b32 s43, v254, 26
	v_readlane_b32 s45, v254, 57
	s_nop 4
	global_load_dwordx4 v[2:5], v0, s[44:45] offset:48
	global_load_dwordx4 v[10:13], v0, s[44:45] offset:32
	global_load_dwordx4 v[18:21], v0, s[44:45] offset:16
	global_load_dwordx4 v[30:33], v0, s[44:45]
	global_load_dwordx4 v[34:37], v0, s[44:45] offset:176
	global_load_dwordx4 v[38:41], v0, s[44:45] offset:160
	global_load_dwordx4 v[42:45], v0, s[44:45] offset:144
	global_load_dwordx4 v[46:49], v0, s[44:45] offset:128
	v_lshl_add_u64 v[26:27], v[6:7], 2, s[42:43]
	global_load_dwordx4 v[6:9], v[26:27], off offset:48
	global_load_dwordx4 v[22:25], v[26:27], off offset:32
	global_load_dwordx4 v[62:65], v[58:59], off offset:96
	global_load_dwordx4 v[14:17], v[26:27], off offset:16
	s_nop 0
	global_load_dwordx4 v[26:29], v[26:27], off
	s_nop 0
	global_load_dwordx4 v[58:61], v[58:59], off offset:112
	s_waitcnt vmcnt(19)
	v_and_b32_e32 v89, 0xffff0000, v69
	v_lshlrev_b32_e32 v88, 16, v69
	v_and_b32_e32 v93, 0xffff0000, v68
	v_lshlrev_b32_e32 v92, 16, v68
	v_and_b32_e32 v97, 0xffff0000, v67
	v_lshlrev_b32_e32 v96, 16, v67
	v_and_b32_e32 v99, 0xffff0000, v66
	v_lshlrev_b32_e32 v98, 16, v66
	s_waitcnt vmcnt(18)
	v_and_b32_e32 v75, 0xffff0000, v73
	v_lshlrev_b32_e32 v74, 16, v73
	v_and_b32_e32 v77, 0xffff0000, v72
	v_lshlrev_b32_e32 v76, 16, v72
	v_and_b32_e32 v79, 0xffff0000, v71
	v_lshlrev_b32_e32 v78, 16, v71
	v_and_b32_e32 v81, 0xffff0000, v70
	v_lshlrev_b32_e32 v80, 16, v70
	s_waitcnt vmcnt(16)
	v_and_b32_e32 v95, 0xffff0000, v57
	v_lshlrev_b32_e32 v94, 16, v57
	global_load_dwordx4 v[66:69], v0, s[44:45] offset:112
	global_load_dwordx4 v[70:73], v0, s[44:45] offset:96
	global_load_dwordx4 v[140:143], v0, s[44:45] offset:80
	global_load_dwordx4 v[144:147], v0, s[44:45] offset:64
	v_and_b32_e32 v161, 0xffff0000, v56
	v_lshlrev_b32_e32 v160, 16, v56
	v_and_b32_e32 v165, 0xffff0000, v55
	v_lshlrev_b32_e32 v164, 16, v55
	v_and_b32_e32 v185, 0xffff0000, v54
	v_lshlrev_b32_e32 v184, 16, v54
	s_waitcnt vmcnt(18)
;     DI bf16_t* fP() const { return (bf16_t*)(ws + WS_P); }
;     DI float* fROPE() const { return (float*)(ws + WS_ROPE); }
; DI void norm_rope64(float* f, const float* g, const float* rope_row) {
;     float ss = 0.f;
; #pragma unroll
;     for (int d = 0; d < 64; ++d) ss += f[d] * f[d];
;     const float rstd = rsqrtf(ss * (1.f / 64.f) + EPS);
; #pragma unroll
;     for (int d = 0; d < 64; ++d) f[d] = f[d] * rstd * g[d];
; DI void attn_item(const Params& p, const Ctx& c, int l, int S, int tokbase, int qb, int kvh) {
;     ...
;         const int kpos = kstart + tid; float f[64];
;         if (kpos >= 0 && kpos < S) {
;             const bf16_t* kp = c.fP() + (size_t)(tokbase + kpos) * P1LD + 512 + kvh * 64;
; #pragma unroll
;             for (int i = 0; i < 8; ++i) unpack8(*(const u32x4*)(kp + 8 * i), f + 8 * i);
;             norm_rope64(f, kg, c.fROPE() + kpos * 16);
	v_and_b32_e32 v189, 0xffff0000, v53
	v_lshlrev_b32_e32 v188, 16, v53
	v_and_b32_e32 v193, 0xffff0000, v52
	v_lshlrev_b32_e32 v192, 16, v52
	v_and_b32_e32 v197, 0xffff0000, v51
	v_lshlrev_b32_e32 v196, 16, v51
	v_and_b32_e32 v201, 0xffff0000, v50
	v_lshlrev_b32_e32 v200, 16, v50
	global_load_dwordx4 v[50:53], v0, s[44:45] offset:240
	global_load_dwordx4 v[54:57], v0, s[44:45] offset:224
	global_load_dwordx4 v[148:151], v0, s[44:45] offset:208
	global_load_dwordx4 v[152:155], v0, s[44:45] offset:192
	v_and_b32_e32 v105, 0xffff0000, v107
	v_lshlrev_b32_e32 v104, 16, v107
	v_and_b32_e32 v107, 0xffff0000, v106
	v_lshlrev_b32_e32 v106, 16, v106
	v_pk_mul_f32 v[158:159], v[106:107], v[106:107]
	v_pk_mul_f32 v[156:157], v[104:105], v[104:105]
	v_add_f32_e32 v1, v158, v159
	v_and_b32_e32 v83, 0xffff0000, v103
	v_lshlrev_b32_e32 v82, 16, v103
	v_and_b32_e32 v85, 0xffff0000, v102
	v_lshlrev_b32_e32 v84, 16, v102
	v_and_b32_e32 v103, 0xffff0000, v108
	v_lshlrev_b32_e32 v102, 16, v108
	v_add_f32_e32 v1, v156, v1
	v_pk_mul_f32 v[136:137], v[102:103], v[102:103]
	v_add_f32_e32 v1, v157, v1
	v_and_b32_e32 v87, 0xffff0000, v101
	v_lshlrev_b32_e32 v86, 16, v101
	v_and_b32_e32 v91, 0xffff0000, v100
	v_lshlrev_b32_e32 v90, 16, v100
	v_and_b32_e32 v101, 0xffff0000, v109
	v_lshlrev_b32_e32 v100, 16, v109
	v_add_f32_e32 v1, v136, v1
	v_pk_mul_f32 v[134:135], v[100:101], v[100:101]
	v_add_f32_e32 v1, v137, v1
	v_add_f32_e32 v1, v134, v1
	v_pk_mul_f32 v[132:133], v[98:99], v[98:99]
	v_add_f32_e32 v1, v135, v1
	v_add_f32_e32 v1, v132, v1
	v_pk_mul_f32 v[130:131], v[96:97], v[96:97]
	v_add_f32_e32 v1, v133, v1
	v_add_f32_e32 v1, v130, v1
	v_pk_mul_f32 v[128:129], v[92:93], v[92:93]
	v_add_f32_e32 v1, v131, v1
	v_add_f32_e32 v1, v128, v1
	v_pk_mul_f32 v[124:125], v[88:89], v[88:89]
	v_add_f32_e32 v1, v129, v1
	v_add_f32_e32 v1, v124, v1
	v_pk_mul_f32 v[202:203], v[200:201], v[200:201]
	v_add_f32_e32 v1, v125, v1
	v_add_f32_e32 v1, v202, v1
	v_pk_mul_f32 v[198:199], v[196:197], v[196:197]
	v_add_f32_e32 v1, v203, v1
	v_add_f32_e32 v1, v198, v1
	v_pk_mul_f32 v[194:195], v[192:193], v[192:193]
	v_add_f32_e32 v1, v199, v1
	v_add_f32_e32 v1, v194, v1
	v_pk_mul_f32 v[190:191], v[188:189], v[188:189]
	v_add_f32_e32 v1, v195, v1
	v_add_f32_e32 v1, v190, v1
	v_pk_mul_f32 v[186:187], v[184:185], v[184:185]
	v_add_f32_e32 v1, v191, v1
	v_add_f32_e32 v1, v186, v1
	v_pk_mul_f32 v[182:183], v[164:165], v[164:165]
	v_add_f32_e32 v1, v187, v1
	v_add_f32_e32 v1, v182, v1
	v_pk_mul_f32 v[162:163], v[160:161], v[160:161]
	v_add_f32_e32 v1, v183, v1
	v_add_f32_e32 v1, v162, v1
	v_pk_mul_f32 v[126:127], v[94:95], v[94:95]
	v_add_f32_e32 v1, v163, v1
	v_add_f32_e32 v1, v126, v1
	v_pk_mul_f32 v[122:123], v[90:91], v[90:91]
	v_add_f32_e32 v1, v127, v1
	v_add_f32_e32 v1, v122, v1
	v_pk_mul_f32 v[120:121], v[86:87], v[86:87]
	v_add_f32_e32 v1, v123, v1
	v_add_f32_e32 v1, v120, v1
	v_pk_mul_f32 v[118:119], v[84:85], v[84:85]
	v_add_f32_e32 v1, v121, v1
	v_add_f32_e32 v1, v118, v1
	v_pk_mul_f32 v[116:117], v[82:83], v[82:83]
	v_add_f32_e32 v1, v119, v1
	v_add_f32_e32 v1, v116, v1
	v_pk_mul_f32 v[114:115], v[80:81], v[80:81]
	v_add_f32_e32 v1, v117, v1
	v_add_f32_e32 v1, v114, v1
	v_pk_mul_f32 v[112:113], v[78:79], v[78:79]
	v_add_f32_e32 v1, v115, v1
	v_add_f32_e32 v1, v112, v1
	v_pk_mul_f32 v[110:111], v[76:77], v[76:77]
	v_add_f32_e32 v1, v113, v1
	v_add_f32_e32 v1, v110, v1
	v_pk_mul_f32 v[108:109], v[74:75], v[74:75]
	v_add_f32_e32 v1, v111, v1
	s_waitcnt vmcnt(11)
	v_lshlrev_b32_e32 v216, 16, v62
	v_and_b32_e32 v217, 0xffff0000, v62
	v_add_f32_e32 v1, v108, v1
	v_pk_mul_f32 v[218:219], v[216:217], v[216:217]
	v_add_f32_e32 v1, v109, v1
	v_lshlrev_b32_e32 v62, 16, v63
	v_and_b32_e32 v63, 0xffff0000, v63
	v_add_f32_e32 v1, v218, v1
	v_pk_mul_f32 v[220:221], v[62:63], v[62:63]
	v_add_f32_e32 v1, v219, v1
	v_lshlrev_b32_e32 v222, 16, v64
	v_and_b32_e32 v223, 0xffff0000, v64
	v_add_f32_e32 v1, v220, v1
	v_pk_mul_f32 v[224:225], v[222:223], v[222:223]
	v_add_f32_e32 v1, v221, v1
	v_lshlrev_b32_e32 v64, 16, v65
	v_and_b32_e32 v65, 0xffff0000, v65
	v_add_f32_e32 v1, v224, v1
	v_pk_mul_f32 v[226:227], v[64:65], v[64:65]
	v_add_f32_e32 v1, v225, v1
	s_waitcnt vmcnt(8)
	v_lshlrev_b32_e32 v228, 16, v58
	v_and_b32_e32 v229, 0xffff0000, v58
	v_add_f32_e32 v1, v226, v1
	v_pk_mul_f32 v[230:231], v[228:229], v[228:229]
	v_add_f32_e32 v1, v227, v1
	v_lshlrev_b32_e32 v58, 16, v59
	v_and_b32_e32 v59, 0xffff0000, v59
	v_add_f32_e32 v1, v230, v1
	v_pk_mul_f32 v[232:233], v[58:59], v[58:59]
	v_add_f32_e32 v1, v231, v1
	v_lshlrev_b32_e32 v234, 16, v60
	v_and_b32_e32 v235, 0xffff0000, v60
	v_add_f32_e32 v1, v232, v1
	v_pk_mul_f32 v[236:237], v[234:235], v[234:235]
	v_add_f32_e32 v1, v233, v1
	v_lshlrev_b32_e32 v60, 16, v61
	v_and_b32_e32 v61, 0xffff0000, v61
	v_add_f32_e32 v1, v236, v1
	v_pk_mul_f32 v[238:239], v[60:61], v[60:61]
	v_add_f32_e32 v1, v237, v1
	v_add_f32_e32 v1, v238, v1
	v_add_f32_e32 v1, v239, v1
	v_fmamk_f32 v1, v1, 0x3c800000, v205
	v_mul_f32_e32 v108, 0x4b800000, v1
	v_cmp_gt_f32_e32 vcc, s79, v1
	s_nop 1
	v_cndmask_b32_e32 v1, v1, v108, vcc
	v_rsq_f32_e32 v1, v1
	s_nop 0
	v_mul_f32_e32 v108, 0x45800000, v1
	v_cndmask_b32_e32 v108, v1, v108, vcc
	v_pk_mul_f32 v[58:59], v[108:109], v[58:59] op_sel_hi:[0,1]
	v_pk_mul_f32 v[106:107], v[108:109], v[106:107] op_sel_hi:[0,1]
	v_pk_mul_f32 v[98:99], v[108:109], v[98:99] op_sel_hi:[0,1]
	s_waitcnt vmcnt(2)
; #define LAS __attribute__((address_space(3)))
; DI u32x4 pack8(const float* f) { u32x4 w; w.x = pk2(f[0], f[1]); w.y = pk2(f[2], f[3]); w.z = pk2(f[4], f[5]); w.w = pk2(f[6], f[7]); return w; }
; DI void norm_rope64(float* f, const float* g, const float* rope_row) {
;     ...
;     for (int d = 0; d < 64; ++d) f[d] = f[d] * rstd * g[d];
; #pragma unroll
;     for (int i = 0; i < 8; ++i) { const float cs = rope_row[i], sn = rope_row[8 + i], x1 = f[i], x2 = f[8 + i]; f[i] = x1 * cs - x2 * sn; f[8 + i] = x2 * cs + x1 * sn; }
; DI void attn_item(const Params& p, const Ctx& c, int l, int S, int tokbase, int qb, int kvh) {
;     ...
;         for (int i = 0; i < 8; ++i) *(LAS u32x4*)(Ks + tid * KP + 8 * i) = pack8(f + 8 * i);
	v_pk_mul_f32 v[56:57], v[56:57], v[58:59]
	v_pk_mul_f32 v[58:59], v[108:109], v[234:235] op_sel_hi:[0,1]
	v_pk_mul_f32 v[30:31], v[30:31], v[106:107]
	v_pk_mul_f32 v[104:105], v[108:109], v[104:105] op_sel_hi:[0,1]
	v_pk_mul_f32 v[10:11], v[10:11], v[98:99]
	v_pk_mul_f32 v[96:97], v[108:109], v[96:97] op_sel_hi:[0,1]
	v_pk_mul_f32 v[50:51], v[50:51], v[58:59]
	v_pk_mul_f32 v[58:59], v[108:109], v[60:61] op_sel_hi:[0,1]
	v_pk_mul_f32 v[32:33], v[32:33], v[104:105]
	v_pk_mul_f32 v[102:103], v[108:109], v[102:103] op_sel_hi:[0,1]
	v_pk_mul_f32 v[100:101], v[108:109], v[100:101] op_sel_hi:[0,1]
	v_pk_mul_f32 v[12:13], v[12:13], v[96:97]
	v_pk_mul_f32 v[92:93], v[108:109], v[92:93] op_sel_hi:[0,1]
	v_pk_mul_f32 v[52:53], v[52:53], v[58:59]
	v_pk_mul_f32 v[58:59], v[22:23], v[30:31]
	v_pk_mul_f32 v[22:23], v[22:23], v[10:11]
	v_pk_mul_f32 v[18:19], v[18:19], v[102:103]
	v_pk_mul_f32 v[20:21], v[20:21], v[100:101]
	v_pk_mul_f32 v[2:3], v[2:3], v[92:93]
	v_pk_mul_f32 v[88:89], v[108:109], v[88:89] op_sel_hi:[0,1]
	v_pk_mul_f32 v[100:101], v[108:109], v[184:185] op_sel_hi:[0,1]
	v_pk_fma_f32 v[22:23], v[26:27], v[30:31], v[22:23] neg_lo:[0,0,1] neg_hi:[0,0,1]
	v_pk_fma_f32 v[26:27], v[26:27], v[10:11], v[58:59]
	v_pk_mul_f32 v[10:11], v[32:33], v[24:25]
	v_pk_mul_f32 v[24:25], v[12:13], v[24:25]
	v_pk_mul_f32 v[4:5], v[4:5], v[88:89]
	v_pk_mul_f32 v[70:71], v[70:71], v[100:101]
	v_pk_mul_f32 v[100:101], v[108:109], v[164:165] op_sel_hi:[0,1]
	v_pk_mul_f32 v[78:79], v[108:109], v[78:79] op_sel_hi:[0,1]
	v_pk_mul_f32 v[76:77], v[108:109], v[76:77] op_sel_hi:[0,1]
	v_pk_mul_f32 v[74:75], v[108:109], v[74:75] op_sel_hi:[0,1]
	v_pk_fma_f32 v[24:25], v[32:33], v[28:29], v[24:25] neg_lo:[0,0,1] neg_hi:[0,0,1]
	v_pk_fma_f32 v[28:29], v[12:13], v[28:29], v[10:11]
	v_pk_mul_f32 v[10:11], v[18:19], v[6:7]
	v_pk_mul_f32 v[6:7], v[2:3], v[6:7]
	v_pk_mul_f32 v[88:89], v[108:109], v[200:201] op_sel_hi:[0,1]
	v_pk_mul_f32 v[92:93], v[108:109], v[196:197] op_sel_hi:[0,1]
	v_pk_mul_f32 v[96:97], v[108:109], v[192:193] op_sel_hi:[0,1]
	v_pk_mul_f32 v[98:99], v[108:109], v[188:189] op_sel_hi:[0,1]
	v_pk_mul_f32 v[72:73], v[72:73], v[100:101]
	v_pk_mul_f32 v[100:101], v[108:109], v[160:161] op_sel_hi:[0,1]
	v_pk_mul_f32 v[94:95], v[108:109], v[94:95] op_sel_hi:[0,1]
	v_pk_mul_f32 v[90:91], v[108:109], v[90:91] op_sel_hi:[0,1]
	v_pk_mul_f32 v[86:87], v[108:109], v[86:87] op_sel_hi:[0,1]
	v_pk_mul_f32 v[84:85], v[108:109], v[84:85] op_sel_hi:[0,1]
	v_pk_mul_f32 v[82:83], v[108:109], v[82:83] op_sel_hi:[0,1]
	v_pk_mul_f32 v[80:81], v[108:109], v[80:81] op_sel_hi:[0,1]
	v_pk_mul_f32 v[40:41], v[40:41], v[78:79]
	v_pk_mul_f32 v[34:35], v[34:35], v[76:77]
	v_pk_mul_f32 v[36:37], v[36:37], v[74:75]
	v_pk_mul_f32 v[74:75], v[108:109], v[216:217] op_sel_hi:[0,1]
	v_pk_mul_f32 v[62:63], v[108:109], v[62:63] op_sel_hi:[0,1]
	v_pk_mul_f32 v[76:77], v[108:109], v[222:223] op_sel_hi:[0,1]
	v_pk_mul_f32 v[64:65], v[108:109], v[64:65] op_sel_hi:[0,1]
	v_pk_mul_f32 v[78:79], v[108:109], v[228:229] op_sel_hi:[0,1]
	v_pk_fma_f32 v[6:7], v[18:19], v[14:15], v[6:7] neg_lo:[0,0,1] neg_hi:[0,0,1]
	v_pk_fma_f32 v[14:15], v[2:3], v[14:15], v[10:11]
	v_pk_mul_f32 v[2:3], v[20:21], v[8:9]
	v_pk_mul_f32 v[8:9], v[4:5], v[8:9]
	v_pk_mul_f32 v[88:89], v[144:145], v[88:89]
	v_pk_mul_f32 v[92:93], v[146:147], v[92:93]
	v_pk_mul_f32 v[96:97], v[140:141], v[96:97]
	v_pk_mul_f32 v[98:99], v[142:143], v[98:99]
	v_pk_mul_f32 v[66:67], v[66:67], v[100:101]
	v_pk_mul_f32 v[68:69], v[68:69], v[94:95]
	v_pk_mul_f32 v[46:47], v[46:47], v[90:91]
	v_pk_mul_f32 v[48:49], v[48:49], v[86:87]
	v_pk_mul_f32 v[42:43], v[42:43], v[84:85]
	v_pk_mul_f32 v[44:45], v[44:45], v[82:83]
	v_pk_mul_f32 v[38:39], v[38:39], v[80:81]
	s_waitcnt vmcnt(0)
	v_pk_mul_f32 v[74:75], v[152:153], v[74:75]
	v_pk_mul_f32 v[62:63], v[154:155], v[62:63]
	v_pk_mul_f32 v[76:77], v[148:149], v[76:77]
	v_pk_mul_f32 v[64:65], v[150:151], v[64:65]
	v_pk_mul_f32 v[54:55], v[54:55], v[78:79]
	v_pk_fma_f32 v[8:9], v[20:21], v[16:17], v[8:9] neg_lo:[0,0,1] neg_hi:[0,0,1]
	v_pk_fma_f32 v[16:17], v[4:5], v[16:17], v[2:3]
	v_cvt_pk_bf16_f32 v10, v22, v23
	v_cvt_pk_bf16_f32 v11, v24, v25
	v_cvt_pk_bf16_f32 v12, v6, v7
	v_cvt_pk_bf16_f32 v13, v8, v9
	v_cvt_pk_bf16_f32 v2, v26, v27
	v_cvt_pk_bf16_f32 v3, v28, v29
	v_cvt_pk_bf16_f32 v4, v14, v15
	v_cvt_pk_bf16_f32 v5, v16, v17
	v_cvt_pk_bf16_f32 v26, v88, v89
	v_cvt_pk_bf16_f32 v27, v92, v93
	v_cvt_pk_bf16_f32 v28, v96, v97
	v_cvt_pk_bf16_f32 v29, v98, v99
	v_cvt_pk_bf16_f32 v18, v70, v71
	v_cvt_pk_bf16_f32 v19, v72, v73
	v_cvt_pk_bf16_f32 v20, v66, v67
	v_cvt_pk_bf16_f32 v21, v68, v69
	v_cvt_pk_bf16_f32 v14, v46, v47
	v_cvt_pk_bf16_f32 v15, v48, v49
	v_cvt_pk_bf16_f32 v16, v42, v43
	v_cvt_pk_bf16_f32 v17, v44, v45
	v_cvt_pk_bf16_f32 v6, v38, v39
	v_cvt_pk_bf16_f32 v7, v40, v41
	v_cvt_pk_bf16_f32 v8, v34, v35
	v_cvt_pk_bf16_f32 v9, v36, v37
	v_cvt_pk_bf16_f32 v22, v74, v75
	v_cvt_pk_bf16_f32 v23, v62, v63
	v_cvt_pk_bf16_f32 v24, v76, v77
	v_cvt_pk_bf16_f32 v25, v64, v65
	v_cvt_pk_bf16_f32 v30, v54, v55
	v_cvt_pk_bf16_f32 v31, v56, v57
	v_cvt_pk_bf16_f32 v32, v50, v51
	v_cvt_pk_bf16_f32 v33, v52, v53
